# s20 + p0_wt: P0 normalised rows / transposed weights written through (nothing dirty left for barrier 0's L2 write-back)
# speedup vs baseline: 1.0033x; 1.0033x over previous
.LBB0_11:
	s_cmpk_gt_i32 s15, 0xaff
	s_mov_b64 s[6:7], -1
	s_cbranch_scc0 .LBB0_13
	s_and_b32 s7, s10, 0x1ffc0
	s_and_b32 s6, s8, 0x3e0
	v_or_b32_e32 v2, s7, v1
	s_lshl_b32 s0, s6, 2
	v_lshl_add_u64 v[32:33], v[4:5], 0, s[0:1]
	v_lshlrev_b32_e32 v2, 12, v2
	v_lshl_add_u64 v[60:61], v[32:33], 0, v[2:3]
	v_add_co_u32_e32 v36, vcc, 0x8000, v60
	v_or_b32_e32 v2, s6, v1
	s_nop 0
	v_addc_co_u32_e32 v37, vcc, 0, v61, vcc
	v_add_co_u32_e32 v40, vcc, 0x10000, v60
	global_load_dwordx4 v[32:35], v[60:61], off nt
	s_nop 0
	global_load_dwordx4 v[36:39], v[36:37], off nt
	v_addc_co_u32_e32 v41, vcc, 0, v61, vcc
	v_add_co_u32_e32 v44, vcc, 0x18000, v60
	s_lshl_b32 s0, s7, 1
	s_nop 0
	v_addc_co_u32_e32 v45, vcc, 0, v61, vcc
	v_add_co_u32_e32 v48, vcc, 0x20000, v60
	global_load_dwordx4 v[40:43], v[40:41], off nt
	s_nop 0
	global_load_dwordx4 v[44:47], v[44:45], off nt
	v_addc_co_u32_e32 v49, vcc, 0, v61, vcc
	v_add_co_u32_e32 v52, vcc, 0x28000, v60
	v_lshl_add_u64 v[64:65], v[6:7], 0, s[0:1]
	s_nop 0
	v_addc_co_u32_e32 v53, vcc, 0, v61, vcc
	global_load_dwordx4 v[48:51], v[48:49], off nt
	s_nop 0
	global_load_dwordx4 v[52:55], v[52:53], off nt
	v_add_co_u32_e32 v56, vcc, 0x30000, v60
	v_lshlrev_b32_e32 v2, 11, v2
	s_nop 0
	v_addc_co_u32_e32 v57, vcc, 0, v61, vcc
	global_load_dwordx4 v[56:59], v[56:57], off nt
	v_add_co_u32_e32 v60, vcc, 0x38000, v60
	s_nop 1
	v_addc_co_u32_e32 v61, vcc, 0, v61, vcc
	global_load_dwordx4 v[60:63], v[60:61], off nt
	s_waitcnt vmcnt(7)
	ds_write2_b32 v16, v32, v33 offset1:1
	ds_write2_b32 v16, v34, v35 offset0:2 offset1:3
	s_waitcnt vmcnt(6)
	ds_write2_b32 v17, v36, v37 offset1:1
	ds_write2_b32 v18, v38, v39 offset1:1
	s_waitcnt vmcnt(5)
	ds_write2_b32 v19, v40, v41 offset1:1
	ds_write2_b32 v20, v42, v43 offset1:1
	s_waitcnt vmcnt(4)
	ds_write2_b32 v21, v44, v45 offset1:1
	ds_write2_b32 v22, v46, v47 offset1:1
	s_waitcnt vmcnt(3)
	ds_write2_b32 v23, v48, v49 offset1:1
	ds_write2_b32 v24, v50, v51 offset1:1
	s_waitcnt vmcnt(2)
	ds_write2_b32 v25, v52, v53 offset1:1
	ds_write2_b32 v26, v54, v55 offset1:1
	s_waitcnt vmcnt(1)
	ds_write2_b32 v27, v56, v57 offset1:1
	ds_write2_b32 v28, v58, v59 offset1:1
	s_waitcnt vmcnt(0)
	ds_write2_b32 v29, v60, v61 offset1:1
	ds_write2_b32 v30, v62, v63 offset1:1
	s_waitcnt lgkmcnt(0)
	ds_read2_b32 v[36:37], v15 offset0:33 offset1:41
	ds_read2_b32 v[38:39], v15 offset1:8
	ds_read2_b32 v[40:41], v15 offset0:66 offset1:74
	ds_read2_b32 v[42:43], v15 offset0:99 offset1:107
	ds_read2_b32 v[44:45], v15 offset0:132 offset1:140
	ds_read2_b32 v[46:47], v15 offset0:165 offset1:173
	ds_read2_b32 v[48:49], v15 offset0:198 offset1:206
	ds_read2_b32 v[50:51], v15 offset0:231 offset1:239
	s_waitcnt lgkmcnt(6)
	v_bfe_u32 v31, v38, 16, 1
	v_bfe_u32 v32, v36, 16, 1
	s_waitcnt lgkmcnt(5)
	v_bfe_u32 v33, v40, 16, 1
	s_waitcnt lgkmcnt(3)
	v_bfe_u32 v35, v44, 16, 1
	s_waitcnt lgkmcnt(2)
	v_bfe_u32 v52, v46, 16, 1
	s_waitcnt lgkmcnt(1)
	v_bfe_u32 v53, v48, 16, 1
	v_add3_u32 v31, v38, v31, s12
	v_bfe_u32 v34, v42, 16, 1
	s_waitcnt lgkmcnt(0)
	v_bfe_u32 v54, v50, 16, 1
	v_add3_u32 v32, v36, v32, s12
	v_add3_u32 v33, v40, v33, s12
	v_add3_u32 v35, v44, v35, s12
	v_add3_u32 v36, v46, v52, s12
	v_add3_u32 v38, v48, v53, s12
	v_lshrrev_b32_e32 v31, 16, v31
	v_lshl_add_u64 v[52:53], v[64:65], 0, v[2:3]
	v_bfe_u32 v2, v39, 16, 1
	v_add3_u32 v34, v42, v34, s12
	v_add3_u32 v40, v50, v54, s12
	v_lshrrev_b32_e32 v33, 16, v33
	v_lshrrev_b32_e32 v35, 16, v35
	v_lshrrev_b32_e32 v38, 16, v38
	v_and_or_b32 v32, v32, s13, v31
	v_add3_u32 v2, v39, v2, s12
	v_bfe_u32 v31, v37, 16, 1
	v_and_or_b32 v33, v34, s13, v33
	v_and_or_b32 v34, v36, s13, v35
	v_and_or_b32 v35, v40, s13, v38
	v_lshrrev_b32_e32 v2, 16, v2
	v_add3_u32 v31, v37, v31, s12
	global_store_dwordx4 v[52:53], v[32:35], off sc1
	ds_read2_b32 v[36:37], v15 offset0:16 offset1:24
	s_nop 0
	v_and_or_b32 v32, v31, s13, v2
	v_bfe_u32 v2, v41, 16, 1
	v_add3_u32 v2, v41, v2, s12
	v_bfe_u32 v31, v43, 16, 1
	v_lshrrev_b32_e32 v2, 16, v2
	v_add3_u32 v31, v43, v31, s12
	v_and_or_b32 v33, v31, s13, v2
	v_bfe_u32 v2, v45, 16, 1
	v_add3_u32 v2, v45, v2, s12
	v_bfe_u32 v31, v47, 16, 1
	v_lshrrev_b32_e32 v2, 16, v2
	v_add3_u32 v31, v47, v31, s12
	v_and_or_b32 v34, v31, s13, v2
	v_bfe_u32 v2, v49, 16, 1
	v_add3_u32 v2, v49, v2, s12
	v_bfe_u32 v31, v51, 16, 1
	v_lshrrev_b32_e32 v2, 16, v2
	v_add3_u32 v31, v51, v31, s12
	v_and_or_b32 v35, v31, s13, v2
	v_or_b32_e32 v2, s6, v12
	v_lshlrev_b32_e32 v2, 11, v2
	v_lshl_add_u64 v[38:39], v[64:65], 0, v[2:3]
	global_store_dwordx4 v[38:39], v[32:35], off sc1
	ds_read2_b32 v[38:39], v15 offset0:49 offset1:57
	ds_read2_b32 v[40:41], v15 offset0:82 offset1:90
	ds_read2_b32 v[42:43], v15 offset0:115 offset1:123
	s_waitcnt lgkmcnt(3)
	v_bfe_u32 v2, v36, 16, 1
	v_add3_u32 v2, v36, v2, s12
	s_waitcnt lgkmcnt(2)
	v_bfe_u32 v31, v38, 16, 1
	ds_read2_b32 v[44:45], v15 offset0:148 offset1:156
	v_lshrrev_b32_e32 v2, 16, v2
	v_add3_u32 v31, v38, v31, s12
	ds_read2_b32 v[46:47], v15 offset0:181 offset1:189
	v_and_or_b32 v32, v31, s13, v2
	s_waitcnt lgkmcnt(3)
	v_bfe_u32 v2, v40, 16, 1
	v_add3_u32 v2, v40, v2, s12
	s_waitcnt lgkmcnt(2)
	v_bfe_u32 v31, v42, 16, 1
	ds_read2_b32 v[48:49], v15 offset0:214 offset1:222
	v_lshrrev_b32_e32 v2, 16, v2
	v_add3_u32 v31, v42, v31, s12
	ds_read2_b32 v[50:51], v15 offset0:247 offset1:255
	v_and_or_b32 v33, v31, s13, v2
	s_waitcnt lgkmcnt(3)
	v_bfe_u32 v2, v44, 16, 1
	v_add3_u32 v2, v44, v2, s12
	s_waitcnt lgkmcnt(2)
	v_bfe_u32 v31, v46, 16, 1
	v_lshrrev_b32_e32 v2, 16, v2
	v_add3_u32 v31, v46, v31, s12
	v_and_or_b32 v34, v31, s13, v2
	s_waitcnt lgkmcnt(1)
	v_bfe_u32 v2, v48, 16, 1
	v_add3_u32 v2, v48, v2, s12
	s_waitcnt lgkmcnt(0)
	v_bfe_u32 v31, v50, 16, 1
	v_lshrrev_b32_e32 v2, 16, v2
	v_add3_u32 v31, v50, v31, s12
	v_and_or_b32 v35, v31, s13, v2
	v_or_b32_e32 v2, s6, v13
	v_lshlrev_b32_e32 v2, 11, v2
	v_lshl_add_u64 v[52:53], v[64:65], 0, v[2:3]
	v_or_b32_e32 v2, s6, v14
	v_lshlrev_b32_e32 v2, 11, v2
	v_bfe_u32 v31, v37, 16, 1
	global_store_dwordx4 v[52:53], v[32:35], off sc1
	v_lshl_add_u64 v[52:53], v[64:65], 0, v[2:3]
	v_bfe_u32 v2, v39, 16, 1
	v_add3_u32 v31, v37, v31, s12
	v_add3_u32 v2, v39, v2, s12
	v_lshrrev_b32_e32 v31, 16, v31
	v_and_or_b32 v32, v2, s13, v31
	v_bfe_u32 v31, v41, 16, 1
	v_bfe_u32 v2, v43, 16, 1
	v_add3_u32 v31, v41, v31, s12
	v_add3_u32 v2, v43, v2, s12
	v_lshrrev_b32_e32 v31, 16, v31
	v_and_or_b32 v33, v2, s13, v31
	v_bfe_u32 v31, v45, 16, 1
	v_bfe_u32 v2, v47, 16, 1
	v_add3_u32 v31, v45, v31, s12
	v_add3_u32 v2, v47, v2, s12
	v_lshrrev_b32_e32 v31, 16, v31
	v_and_or_b32 v34, v2, s13, v31
	v_bfe_u32 v31, v49, 16, 1
	v_bfe_u32 v2, v51, 16, 1
	v_add3_u32 v31, v49, v31, s12
	v_add3_u32 v2, v51, v2, s12
	v_lshrrev_b32_e32 v31, 16, v31
	v_and_or_b32 v35, v2, s13, v31
	global_store_dwordx4 v[52:53], v[32:35], off sc1
	s_waitcnt lgkmcnt(0)
	s_mov_b64 s[6:7], 0
.LBB0_13:
	s_andn2_b64 vcc, exec, s[6:7]
	s_cbranch_vccnz .LBB0_10
	s_mul_hi_i32 s0, s15, 0x2e8ba2e9
	s_lshr_b32 s6, s0, 31
	s_ashr_i32 s0, s0, 5
	s_add_i32 s0, s0, s6
	s_lshl_b32 s6, s0, 6
	s_mulk_i32 s0, 0xea00
	s_add_i32 s18, s8, s0
	v_or_b32_e32 v2, s6, v1
	s_ashr_i32 s19, s18, 31
	v_lshl_add_u64 v[60:61], s[18:19], 2, v[8:9]
	v_or_b32_e32 v31, 8, v2
	v_mad_i64_i32 v[36:37], s[20:21], v31, s14, v[60:61]
	v_or_b32_e32 v31, 16, v2
	v_mad_i64_i32 v[40:41], s[20:21], v31, s14, v[60:61]
	v_or_b32_e32 v31, 24, v2
	v_mad_i64_i32 v[44:45], s[20:21], v31, s14, v[60:61]
	v_or_b32_e32 v31, 32, v2
	v_mad_i64_i32 v[48:49], s[20:21], v31, s14, v[60:61]
	v_or_b32_e32 v31, 40, v2
	v_mad_i64_i32 v[32:33], s[20:21], v2, s14, v[60:61]
	v_mad_i64_i32 v[52:53], s[20:21], v31, s14, v[60:61]
	global_load_dwordx4 v[32:35], v[32:33], off nt
	s_nop 0
	global_load_dwordx4 v[36:39], v[36:37], off nt
	s_nop 0
	global_load_dwordx4 v[40:43], v[40:41], off nt
	s_nop 0
	global_load_dwordx4 v[44:47], v[44:45], off nt
	s_nop 0
	global_load_dwordx4 v[48:51], v[48:49], off nt
	s_nop 0
	global_load_dwordx4 v[52:55], v[52:53], off nt
	v_or_b32_e32 v31, 48, v2
	v_mad_i64_i32 v[56:57], s[20:21], v31, s14, v[60:61]
	global_load_dwordx4 v[56:59], v[56:57], off nt
	v_or_b32_e32 v2, 56, v2
	v_mad_i64_i32 v[60:61], s[20:21], v2, s14, v[60:61]
	global_load_dwordx4 v[60:63], v[60:61], off nt
	v_add_u32_e32 v66, s18, v1
	s_ashr_i32 s7, s6, 31
	v_ashrrev_i32_e32 v67, 31, v66
	v_lshl_add_u64 v[64:65], s[6:7], 1, v[10:11]
	v_lshlrev_b64 v[68:69], 11, v[66:67]
	v_lshl_add_u64 v[68:69], v[64:65], 0, v[68:69]
	s_waitcnt vmcnt(7)
	ds_write2_b32 v16, v32, v33 offset1:1
	ds_write2_b32 v16, v34, v35 offset0:2 offset1:3
	s_waitcnt vmcnt(6)
	ds_write2_b32 v17, v36, v37 offset1:1
	ds_write2_b32 v18, v38, v39 offset1:1
	s_waitcnt vmcnt(5)
	ds_write2_b32 v19, v40, v41 offset1:1
	ds_write2_b32 v20, v42, v43 offset1:1
	s_waitcnt vmcnt(4)
	ds_write2_b32 v21, v44, v45 offset1:1
	ds_write2_b32 v22, v46, v47 offset1:1
	s_waitcnt vmcnt(3)
	ds_write2_b32 v23, v48, v49 offset1:1
	ds_write2_b32 v24, v50, v51 offset1:1
	s_waitcnt vmcnt(2)
	ds_write2_b32 v25, v52, v53 offset1:1
	ds_write2_b32 v26, v54, v55 offset1:1
	s_waitcnt vmcnt(1)
	ds_write2_b32 v27, v56, v57 offset1:1
	ds_write2_b32 v28, v58, v59 offset1:1
	s_waitcnt vmcnt(0)
	ds_write2_b32 v29, v60, v61 offset1:1
	ds_write2_b32 v30, v62, v63 offset1:1
	s_waitcnt lgkmcnt(0)
	ds_read2_b32 v[36:37], v15 offset0:33 offset1:41
	ds_read2_b32 v[32:33], v15 offset1:8
	ds_read2_b32 v[38:39], v15 offset0:66 offset1:74
	ds_read2_b32 v[40:41], v15 offset0:99 offset1:107
	ds_read2_b32 v[42:43], v15 offset0:132 offset1:140
	ds_read2_b32 v[44:45], v15 offset0:165 offset1:173
	ds_read2_b32 v[46:47], v15 offset0:198 offset1:206
	ds_read2_b32 v[48:49], v15 offset0:231 offset1:239
	s_waitcnt lgkmcnt(6)
	v_bfe_u32 v2, v32, 16, 1
	v_bfe_u32 v31, v36, 16, 1
	s_waitcnt lgkmcnt(5)
	v_bfe_u32 v34, v38, 16, 1
	s_waitcnt lgkmcnt(4)
	v_bfe_u32 v35, v40, 16, 1
	s_waitcnt lgkmcnt(3)
	v_bfe_u32 v50, v42, 16, 1
	s_waitcnt lgkmcnt(1)
	v_bfe_u32 v52, v46, 16, 1
	v_add3_u32 v2, v32, v2, s12
	v_bfe_u32 v51, v44, 16, 1
	s_waitcnt lgkmcnt(0)
	v_bfe_u32 v53, v48, 16, 1
	v_bfe_u32 v54, v33, 16, 1
	v_add3_u32 v31, v36, v31, s12
	v_add3_u32 v32, v38, v34, s12
	v_add3_u32 v34, v40, v35, s12
	v_add3_u32 v35, v42, v50, s12
	v_add3_u32 v38, v46, v52, s12
	v_lshrrev_b32_e32 v2, 16, v2
	v_add3_u32 v36, v44, v51, s12
	v_add3_u32 v40, v48, v53, s12
	v_add3_u32 v33, v33, v54, s12
	v_lshrrev_b32_e32 v42, 16, v32
	v_lshrrev_b32_e32 v35, 16, v35
	v_lshrrev_b32_e32 v38, 16, v38
	v_and_or_b32 v32, v31, s13, v2
	v_bfe_u32 v2, v37, 16, 1
	v_lshrrev_b32_e32 v44, 16, v33
	v_and_or_b32 v33, v34, s13, v42
	v_and_or_b32 v34, v36, s13, v35
	v_and_or_b32 v35, v40, s13, v38
	v_add3_u32 v2, v37, v2, s12
	global_store_dwordx4 v[68:69], v[32:35], off sc1
	v_bfe_u32 v31, v41, 16, 1
	v_add3_u32 v31, v41, v31, s12
	v_and_or_b32 v32, v2, s13, v44
	v_bfe_u32 v2, v39, 16, 1
	v_add3_u32 v2, v39, v2, s12
	v_lshrrev_b32_e32 v2, 16, v2
	v_and_or_b32 v33, v31, s13, v2
	v_bfe_u32 v2, v43, 16, 1
	v_add3_u32 v2, v43, v2, s12
	v_bfe_u32 v31, v45, 16, 1
	v_lshrrev_b32_e32 v2, 16, v2
	v_add3_u32 v31, v45, v31, s12
	v_and_or_b32 v34, v31, s13, v2
	v_bfe_u32 v2, v47, 16, 1
	v_add_u32_e32 v36, 8, v66
	v_add3_u32 v2, v47, v2, s12
	v_bfe_u32 v31, v49, 16, 1
	v_ashrrev_i32_e32 v37, 31, v36
	v_lshrrev_b32_e32 v2, 16, v2
	v_add3_u32 v31, v49, v31, s12
	v_lshlrev_b64 v[36:37], 11, v[36:37]
	v_and_or_b32 v35, v31, s13, v2
	ds_read2_b32 v[38:39], v15 offset0:16 offset1:24
	v_lshl_add_u64 v[36:37], v[64:65], 0, v[36:37]
	global_store_dwordx4 v[36:37], v[32:35], off sc1
	ds_read2_b32 v[36:37], v15 offset0:49 offset1:57
	ds_read2_b32 v[40:41], v15 offset0:82 offset1:90
	ds_read2_b32 v[42:43], v15 offset0:115 offset1:123
	s_waitcnt lgkmcnt(3)
	v_bfe_u32 v2, v38, 16, 1
	v_add3_u32 v2, v38, v2, s12
	s_waitcnt lgkmcnt(2)
	v_bfe_u32 v31, v36, 16, 1
	ds_read2_b32 v[44:45], v15 offset0:148 offset1:156
	v_lshrrev_b32_e32 v2, 16, v2
	v_add3_u32 v31, v36, v31, s12
	ds_read2_b32 v[46:47], v15 offset0:181 offset1:189
	v_and_or_b32 v32, v31, s13, v2
	s_waitcnt lgkmcnt(3)
	v_bfe_u32 v2, v40, 16, 1
	v_add3_u32 v2, v40, v2, s12
	s_waitcnt lgkmcnt(2)
	v_bfe_u32 v31, v42, 16, 1
	ds_read2_b32 v[48:49], v15 offset0:214 offset1:222
	v_lshrrev_b32_e32 v2, 16, v2
	v_add3_u32 v31, v42, v31, s12
	ds_read2_b32 v[50:51], v15 offset0:247 offset1:255
	v_and_or_b32 v33, v31, s13, v2
	s_waitcnt lgkmcnt(3)
	v_bfe_u32 v2, v44, 16, 1
	v_add3_u32 v2, v44, v2, s12
	s_waitcnt lgkmcnt(2)
	v_bfe_u32 v31, v46, 16, 1
	v_lshrrev_b32_e32 v2, 16, v2
	v_add3_u32 v31, v46, v31, s12
	v_and_or_b32 v34, v31, s13, v2
	s_waitcnt lgkmcnt(1)
	v_bfe_u32 v2, v48, 16, 1
	v_add_u32_e32 v52, 16, v66
	v_add3_u32 v2, v48, v2, s12
	s_waitcnt lgkmcnt(0)
	v_bfe_u32 v31, v50, 16, 1
	v_ashrrev_i32_e32 v53, 31, v52
	v_lshrrev_b32_e32 v2, 16, v2
	v_add3_u32 v31, v50, v31, s12
	v_lshlrev_b64 v[52:53], 11, v[52:53]
	v_and_or_b32 v35, v31, s13, v2
	v_lshl_add_u64 v[52:53], v[64:65], 0, v[52:53]
	global_store_dwordx4 v[52:53], v[32:35], off sc1
	v_bfe_u32 v31, v39, 16, 1
	v_bfe_u32 v2, v37, 16, 1
	v_add_u32_e32 v32, 24, v66
	v_ashrrev_i32_e32 v33, 31, v32
	v_add3_u32 v31, v39, v31, s12
	v_lshlrev_b64 v[32:33], 11, v[32:33]
	v_add3_u32 v2, v37, v2, s12
	v_lshrrev_b32_e32 v31, 16, v31
	v_lshl_add_u64 v[52:53], v[64:65], 0, v[32:33]
	v_and_or_b32 v32, v2, s13, v31
	v_bfe_u32 v31, v41, 16, 1
	v_bfe_u32 v2, v43, 16, 1
	v_add3_u32 v31, v41, v31, s12
	v_add3_u32 v2, v43, v2, s12
	v_lshrrev_b32_e32 v31, 16, v31
	v_and_or_b32 v33, v2, s13, v31
	v_bfe_u32 v31, v45, 16, 1
	v_bfe_u32 v2, v47, 16, 1
	v_add3_u32 v31, v45, v31, s12
	v_add3_u32 v2, v47, v2, s12
	v_lshrrev_b32_e32 v31, 16, v31
	v_and_or_b32 v34, v2, s13, v31
	v_bfe_u32 v31, v49, 16, 1
	v_bfe_u32 v2, v51, 16, 1
	v_add3_u32 v31, v49, v31, s12
	v_add3_u32 v2, v51, v2, s12
	v_lshrrev_b32_e32 v31, 16, v31
	v_and_or_b32 v35, v2, s13, v31
	global_store_dwordx4 v[52:53], v[32:35], off sc1
	s_waitcnt lgkmcnt(0)
	s_branch .LBB0_10

.LBB0_17:
	v_mul_f32_e32 v50, v73, v76
	v_bfe_u32 v51, v50, 16, 1
	v_add3_u32 v50, v50, v51, s18
	v_fmamk_f32 v51, v94, 0x3a800000, v1
	v_mul_f32_e32 v54, 0x4b800000, v51
	v_cmp_gt_f32_e32 vcc, s7, v51
	v_bfe_u32 v5, v77, 16, 1
	v_add3_u32 v5, v77, v5, s18
	v_cndmask_b32_e32 v51, v51, v54, vcc
	v_rsq_f32_e32 v51, v51
	v_lshrrev_b32_e32 v5, 16, v5
	v_and_or_b32 v75, v50, s19, v5
	s_add_i32 s0, s0, s6
	v_mul_f32_e32 v5, 0x45800000, v51
	v_cndmask_b32_e32 v50, v51, v5, vcc
	v_pk_mul_f32 v[42:43], v[42:43], v[50:51] op_sel_hi:[1,0]
	v_pk_mul_f32 v[52:53], v[52:53], v[50:51] op_sel_hi:[1,0]
	v_pk_mul_f32 v[42:43], v[58:59], v[42:43]
	v_lshl_add_u64 v[90:91], v[90:91], 0, s[8:9]
	v_and_b32_sdwa v5, v42, v106 dst_sel:DWORD dst_unused:UNUSED_PAD src0_sel:WORD_1 src1_sel:DWORD
	v_add3_u32 v5, v42, v5, s18
	v_and_b32_sdwa v42, v43, v106 dst_sel:DWORD dst_unused:UNUSED_PAD src0_sel:WORD_1 src1_sel:DWORD
	v_add3_u32 v51, v43, v42, s18
	v_pk_mul_f32 v[42:43], v[56:57], v[52:53]
	v_pk_mul_f32 v[44:45], v[44:45], v[50:51] op_sel_hi:[1,0]
	v_and_b32_sdwa v52, v43, v106 dst_sel:DWORD dst_unused:UNUSED_PAD src0_sel:WORD_1 src1_sel:DWORD
	v_add3_u32 v43, v43, v52, s18
	v_and_b32_sdwa v52, v42, v106 dst_sel:DWORD dst_unused:UNUSED_PAD src0_sel:WORD_1 src1_sel:DWORD
	v_add3_u32 v42, v42, v52, s18
	v_and_b32_e32 v43, 0xffff0000, v43
	v_and_b32_e32 v42, 0xffff0000, v42
	v_or_b32_sdwa v43, v43, v51 dst_sel:DWORD dst_unused:UNUSED_PAD src0_sel:DWORD src1_sel:WORD_1
	v_or_b32_sdwa v42, v42, v5 dst_sel:DWORD dst_unused:UNUSED_PAD src0_sel:DWORD src1_sel:WORD_1
	global_store_dwordx2 v[96:97], v[42:43], off offset:2048 sc1
	v_pk_mul_f32 v[42:43], v[46:47], v[50:51] op_sel_hi:[1,0]
	v_pk_mul_f32 v[38:39], v[38:39], v[50:51] op_sel_hi:[1,0]
	v_pk_mul_f32 v[42:43], v[62:63], v[42:43]
	v_pk_mul_f32 v[38:39], v[66:67], v[38:39]
	v_and_b32_sdwa v5, v42, v106 dst_sel:DWORD dst_unused:UNUSED_PAD src0_sel:WORD_1 src1_sel:DWORD
	v_add3_u32 v5, v42, v5, s18
	v_and_b32_sdwa v42, v43, v106 dst_sel:DWORD dst_unused:UNUSED_PAD src0_sel:WORD_1 src1_sel:DWORD
	v_add3_u32 v46, v43, v42, s18
	v_pk_mul_f32 v[42:43], v[60:61], v[44:45]
	v_pk_mul_f32 v[34:35], v[34:35], v[50:51] op_sel_hi:[1,0]
	v_and_b32_sdwa v44, v43, v106 dst_sel:DWORD dst_unused:UNUSED_PAD src0_sel:WORD_1 src1_sel:DWORD
	v_add3_u32 v43, v43, v44, s18
	v_and_b32_sdwa v44, v42, v106 dst_sel:DWORD dst_unused:UNUSED_PAD src0_sel:WORD_1 src1_sel:DWORD
	v_add3_u32 v42, v42, v44, s18
	v_and_b32_e32 v43, 0xffff0000, v43
	v_and_b32_e32 v42, 0xffff0000, v42
	v_or_b32_sdwa v43, v43, v46 dst_sel:DWORD dst_unused:UNUSED_PAD src0_sel:DWORD src1_sel:WORD_1
	v_or_b32_sdwa v42, v42, v5 dst_sel:DWORD dst_unused:UNUSED_PAD src0_sel:DWORD src1_sel:WORD_1
	global_store_dwordx2 v[96:97], v[42:43], off offset:2560 sc1
	v_pk_mul_f32 v[42:43], v[48:49], v[50:51] op_sel_hi:[1,0]
	v_and_b32_sdwa v5, v39, v106 dst_sel:DWORD dst_unused:UNUSED_PAD src0_sel:WORD_1 src1_sel:DWORD
	v_pk_mul_f32 v[42:43], v[64:65], v[42:43]
	v_and_b32_sdwa v44, v38, v106 dst_sel:DWORD dst_unused:UNUSED_PAD src0_sel:WORD_1 src1_sel:DWORD
	v_add3_u32 v38, v38, v44, s18
	v_add3_u32 v5, v39, v5, s18
	v_and_b32_sdwa v39, v43, v106 dst_sel:DWORD dst_unused:UNUSED_PAD src0_sel:WORD_1 src1_sel:DWORD
	v_and_b32_sdwa v44, v42, v106 dst_sel:DWORD dst_unused:UNUSED_PAD src0_sel:WORD_1 src1_sel:DWORD
	v_add3_u32 v39, v43, v39, s18
	v_add3_u32 v42, v42, v44, s18
	v_and_b32_e32 v39, 0xffff0000, v39
	v_and_b32_e32 v42, 0xffff0000, v42
	v_or_b32_sdwa v39, v39, v5 dst_sel:DWORD dst_unused:UNUSED_PAD src0_sel:DWORD src1_sel:WORD_1
	v_or_b32_sdwa v38, v42, v38 dst_sel:DWORD dst_unused:UNUSED_PAD src0_sel:DWORD src1_sel:WORD_1
	global_store_dwordx2 v[96:97], v[38:39], off offset:3072 sc1
	v_pk_mul_f32 v[34:35], v[68:69], v[34:35]
	v_pk_mul_f32 v[38:39], v[40:41], v[50:51] op_sel_hi:[1,0]
	v_mov_b32_e32 v5, v73
	v_pk_mul_f32 v[38:39], v[4:5], v[38:39]
	v_and_b32_sdwa v40, v35, v106 dst_sel:DWORD dst_unused:UNUSED_PAD src0_sel:WORD_1 src1_sel:DWORD
	v_and_b32_sdwa v41, v34, v106 dst_sel:DWORD dst_unused:UNUSED_PAD src0_sel:WORD_1 src1_sel:DWORD
	v_add3_u32 v35, v35, v40, s18
	v_and_b32_sdwa v40, v39, v106 dst_sel:DWORD dst_unused:UNUSED_PAD src0_sel:WORD_1 src1_sel:DWORD
	v_add3_u32 v34, v34, v41, s18
	v_and_b32_sdwa v41, v38, v106 dst_sel:DWORD dst_unused:UNUSED_PAD src0_sel:WORD_1 src1_sel:DWORD
	v_add3_u32 v39, v39, v40, s18
	v_fmamk_f32 v40, v95, 0x3a800000, v1
	v_add3_u32 v38, v38, v41, s18
	v_mul_f32_e32 v41, 0x4b800000, v40
	v_cmp_gt_f32_e32 vcc, s7, v40
	v_and_b32_e32 v39, 0xffff0000, v39
	v_and_b32_e32 v38, 0xffff0000, v38
	v_cndmask_b32_e32 v40, v40, v41, vcc
	v_rsq_f32_e32 v40, v40
	v_or_b32_sdwa v35, v39, v35 dst_sel:DWORD dst_unused:UNUSED_PAD src0_sel:DWORD src1_sel:WORD_1
	v_or_b32_sdwa v34, v38, v34 dst_sel:DWORD dst_unused:UNUSED_PAD src0_sel:DWORD src1_sel:WORD_1
	global_store_dwordx2 v[96:97], v[34:35], off offset:3584 sc1
	v_mul_f32_e32 v34, 0x45800000, v40
	v_cndmask_b32_e32 v34, v40, v34, vcc
	v_pk_mul_f32 v[30:31], v[30:31], v[34:35] op_sel_hi:[1,0]
	v_pk_mul_f32 v[36:37], v[36:37], v[34:35] op_sel_hi:[1,0]
	v_pk_mul_f32 v[30:31], v[58:59], v[30:31]
	v_pk_mul_f32 v[36:37], v[56:57], v[36:37]
	v_and_b32_sdwa v38, v30, v106 dst_sel:DWORD dst_unused:UNUSED_PAD src0_sel:WORD_1 src1_sel:DWORD
	v_and_b32_sdwa v35, v31, v106 dst_sel:DWORD dst_unused:UNUSED_PAD src0_sel:WORD_1 src1_sel:DWORD
	v_add3_u32 v30, v30, v38, s18
	v_and_b32_sdwa v38, v36, v106 dst_sel:DWORD dst_unused:UNUSED_PAD src0_sel:WORD_1 src1_sel:DWORD
	v_add3_u32 v31, v31, v35, s18
	v_and_b32_sdwa v35, v37, v106 dst_sel:DWORD dst_unused:UNUSED_PAD src0_sel:WORD_1 src1_sel:DWORD
	v_add3_u32 v36, v36, v38, s18
	v_add3_u32 v35, v37, v35, s18
	v_and_b32_e32 v36, 0xffff0000, v36
	v_and_b32_e32 v35, 0xffff0000, v35
	v_or_b32_sdwa v30, v36, v30 dst_sel:DWORD dst_unused:UNUSED_PAD src0_sel:DWORD src1_sel:WORD_1
	v_add_co_u32_e32 v36, vcc, s1, v96
	v_or_b32_sdwa v31, v35, v31 dst_sel:DWORD dst_unused:UNUSED_PAD src0_sel:DWORD src1_sel:WORD_1
	s_nop 0
	v_addc_co_u32_e32 v37, vcc, 0, v97, vcc
	v_pk_mul_f32 v[26:27], v[26:27], v[34:35] op_sel_hi:[1,0]
	global_store_dwordx2 v[36:37], v[30:31], off sc1
	v_pk_mul_f32 v[26:27], v[62:63], v[26:27]
	v_pk_mul_f32 v[30:31], v[32:33], v[34:35] op_sel_hi:[1,0]
	v_and_b32_sdwa v32, v27, v106 dst_sel:DWORD dst_unused:UNUSED_PAD src0_sel:WORD_1 src1_sel:DWORD
	v_pk_mul_f32 v[30:31], v[60:61], v[30:31]
	v_and_b32_sdwa v33, v26, v106 dst_sel:DWORD dst_unused:UNUSED_PAD src0_sel:WORD_1 src1_sel:DWORD
	v_add3_u32 v26, v26, v33, s18
	v_add3_u32 v27, v27, v32, s18
	v_and_b32_sdwa v32, v31, v106 dst_sel:DWORD dst_unused:UNUSED_PAD src0_sel:WORD_1 src1_sel:DWORD
	v_and_b32_sdwa v33, v30, v106 dst_sel:DWORD dst_unused:UNUSED_PAD src0_sel:WORD_1 src1_sel:DWORD
	v_add3_u32 v31, v31, v32, s18
	v_add3_u32 v30, v30, v33, s18
	v_and_b32_e32 v31, 0xffff0000, v31
	v_and_b32_e32 v30, 0xffff0000, v30
	v_or_b32_sdwa v27, v31, v27 dst_sel:DWORD dst_unused:UNUSED_PAD src0_sel:DWORD src1_sel:WORD_1
	v_or_b32_sdwa v26, v30, v26 dst_sel:DWORD dst_unused:UNUSED_PAD src0_sel:DWORD src1_sel:WORD_1
	v_pk_mul_f32 v[22:23], v[22:23], v[34:35] op_sel_hi:[1,0]
	global_store_dwordx2 v[36:37], v[26:27], off offset:512 sc1
	v_pk_mul_f32 v[22:23], v[66:67], v[22:23]
	v_pk_mul_f32 v[26:27], v[28:29], v[34:35] op_sel_hi:[1,0]
	v_and_b32_sdwa v28, v23, v106 dst_sel:DWORD dst_unused:UNUSED_PAD src0_sel:WORD_1 src1_sel:DWORD
	v_pk_mul_f32 v[26:27], v[64:65], v[26:27]
	v_and_b32_sdwa v29, v22, v106 dst_sel:DWORD dst_unused:UNUSED_PAD src0_sel:WORD_1 src1_sel:DWORD
	v_add3_u32 v22, v22, v29, s18
	v_add3_u32 v23, v23, v28, s18
	v_and_b32_sdwa v28, v27, v106 dst_sel:DWORD dst_unused:UNUSED_PAD src0_sel:WORD_1 src1_sel:DWORD
	v_and_b32_sdwa v29, v26, v106 dst_sel:DWORD dst_unused:UNUSED_PAD src0_sel:WORD_1 src1_sel:DWORD
	v_add3_u32 v27, v27, v28, s18
	v_add3_u32 v26, v26, v29, s18
	v_and_b32_e32 v27, 0xffff0000, v27
	v_and_b32_e32 v26, 0xffff0000, v26
	v_or_b32_sdwa v23, v27, v23 dst_sel:DWORD dst_unused:UNUSED_PAD src0_sel:DWORD src1_sel:WORD_1
	v_or_b32_sdwa v22, v26, v22 dst_sel:DWORD dst_unused:UNUSED_PAD src0_sel:DWORD src1_sel:WORD_1
	v_pk_mul_f32 v[18:19], v[18:19], v[34:35] op_sel_hi:[1,0]
	global_store_dwordx2 v[36:37], v[22:23], off offset:1024 sc1
	v_pk_mul_f32 v[18:19], v[68:69], v[18:19]
	v_pk_mul_f32 v[22:23], v[24:25], v[34:35] op_sel_hi:[1,0]
	v_and_b32_sdwa v24, v19, v106 dst_sel:DWORD dst_unused:UNUSED_PAD src0_sel:WORD_1 src1_sel:DWORD
	v_pk_mul_f32 v[22:23], v[4:5], v[22:23]
	v_and_b32_sdwa v25, v18, v106 dst_sel:DWORD dst_unused:UNUSED_PAD src0_sel:WORD_1 src1_sel:DWORD
	v_add3_u32 v19, v19, v24, s18
	v_and_b32_sdwa v24, v23, v106 dst_sel:DWORD dst_unused:UNUSED_PAD src0_sel:WORD_1 src1_sel:DWORD
	v_add3_u32 v18, v18, v25, s18
	v_and_b32_sdwa v25, v22, v106 dst_sel:DWORD dst_unused:UNUSED_PAD src0_sel:WORD_1 src1_sel:DWORD
	v_add3_u32 v23, v23, v24, s18
	v_fmamk_f32 v24, v107, 0x3a800000, v1
	v_add3_u32 v22, v22, v25, s18
	v_mul_f32_e32 v25, 0x4b800000, v24
	v_cmp_gt_f32_e32 vcc, s7, v24
	v_and_b32_e32 v23, 0xffff0000, v23
	v_and_b32_e32 v22, 0xffff0000, v22
	v_cndmask_b32_e32 v24, v24, v25, vcc
	v_rsq_f32_e32 v24, v24
	v_or_b32_sdwa v19, v23, v19 dst_sel:DWORD dst_unused:UNUSED_PAD src0_sel:DWORD src1_sel:WORD_1
	v_or_b32_sdwa v18, v22, v18 dst_sel:DWORD dst_unused:UNUSED_PAD src0_sel:DWORD src1_sel:WORD_1
	global_store_dwordx2 v[36:37], v[18:19], off offset:1536 sc1
	v_mul_f32_e32 v18, 0x45800000, v24
	v_cndmask_b32_e32 v18, v24, v18, vcc
	v_pk_mul_f32 v[14:15], v[14:15], v[18:19] op_sel_hi:[1,0]
	v_pk_mul_f32 v[20:21], v[20:21], v[18:19] op_sel_hi:[1,0]
	v_pk_mul_f32 v[14:15], v[58:59], v[14:15]
	v_pk_mul_f32 v[20:21], v[56:57], v[20:21]
	v_and_b32_sdwa v19, v15, v106 dst_sel:DWORD dst_unused:UNUSED_PAD src0_sel:WORD_1 src1_sel:DWORD
	v_and_b32_sdwa v22, v14, v106 dst_sel:DWORD dst_unused:UNUSED_PAD src0_sel:WORD_1 src1_sel:DWORD
	v_add3_u32 v14, v14, v22, s18
	v_add3_u32 v15, v15, v19, s18
	v_and_b32_sdwa v19, v21, v106 dst_sel:DWORD dst_unused:UNUSED_PAD src0_sel:WORD_1 src1_sel:DWORD
	v_and_b32_sdwa v22, v20, v106 dst_sel:DWORD dst_unused:UNUSED_PAD src0_sel:WORD_1 src1_sel:DWORD
	v_add3_u32 v19, v21, v19, s18
	v_add3_u32 v20, v20, v22, s18
	v_and_b32_e32 v19, 0xffff0000, v19
	v_and_b32_e32 v20, 0xffff0000, v20
	v_or_b32_sdwa v15, v19, v15 dst_sel:DWORD dst_unused:UNUSED_PAD src0_sel:DWORD src1_sel:WORD_1
	v_or_b32_sdwa v14, v20, v14 dst_sel:DWORD dst_unused:UNUSED_PAD src0_sel:DWORD src1_sel:WORD_1
	v_pk_mul_f32 v[10:11], v[10:11], v[18:19] op_sel_hi:[1,0]
	global_store_dwordx2 v[36:37], v[14:15], off offset:2048 sc1
	v_pk_mul_f32 v[10:11], v[62:63], v[10:11]
	v_pk_mul_f32 v[14:15], v[16:17], v[18:19] op_sel_hi:[1,0]
	v_and_b32_sdwa v16, v11, v106 dst_sel:DWORD dst_unused:UNUSED_PAD src0_sel:WORD_1 src1_sel:DWORD
	v_pk_mul_f32 v[14:15], v[60:61], v[14:15]
	v_and_b32_sdwa v17, v10, v106 dst_sel:DWORD dst_unused:UNUSED_PAD src0_sel:WORD_1 src1_sel:DWORD
	v_add3_u32 v10, v10, v17, s18
	v_add3_u32 v11, v11, v16, s18
	v_and_b32_sdwa v16, v15, v106 dst_sel:DWORD dst_unused:UNUSED_PAD src0_sel:WORD_1 src1_sel:DWORD
	v_and_b32_sdwa v17, v14, v106 dst_sel:DWORD dst_unused:UNUSED_PAD src0_sel:WORD_1 src1_sel:DWORD
	v_add3_u32 v15, v15, v16, s18
	v_add3_u32 v14, v14, v17, s18
	v_and_b32_e32 v15, 0xffff0000, v15
	v_and_b32_e32 v14, 0xffff0000, v14
	v_or_b32_sdwa v11, v15, v11 dst_sel:DWORD dst_unused:UNUSED_PAD src0_sel:DWORD src1_sel:WORD_1
	v_or_b32_sdwa v10, v14, v10 dst_sel:DWORD dst_unused:UNUSED_PAD src0_sel:DWORD src1_sel:WORD_1
	v_pk_mul_f32 v[6:7], v[6:7], v[18:19] op_sel_hi:[1,0]
	global_store_dwordx2 v[36:37], v[10:11], off offset:2560 sc1
	v_pk_mul_f32 v[6:7], v[66:67], v[6:7]
	v_pk_mul_f32 v[10:11], v[12:13], v[18:19] op_sel_hi:[1,0]
	v_and_b32_sdwa v12, v7, v106 dst_sel:DWORD dst_unused:UNUSED_PAD src0_sel:WORD_1 src1_sel:DWORD
	v_pk_mul_f32 v[10:11], v[64:65], v[10:11]
	v_and_b32_sdwa v13, v6, v106 dst_sel:DWORD dst_unused:UNUSED_PAD src0_sel:WORD_1 src1_sel:DWORD
	v_add3_u32 v6, v6, v13, s18
	v_add3_u32 v7, v7, v12, s18
	v_and_b32_sdwa v12, v11, v106 dst_sel:DWORD dst_unused:UNUSED_PAD src0_sel:WORD_1 src1_sel:DWORD
	v_and_b32_sdwa v13, v10, v106 dst_sel:DWORD dst_unused:UNUSED_PAD src0_sel:WORD_1 src1_sel:DWORD
	v_add3_u32 v11, v11, v12, s18
	v_add3_u32 v10, v10, v13, s18
	v_and_b32_e32 v11, 0xffff0000, v11
	v_and_b32_e32 v10, 0xffff0000, v10
	v_or_b32_sdwa v7, v11, v7 dst_sel:DWORD dst_unused:UNUSED_PAD src0_sel:DWORD src1_sel:WORD_1
	v_or_b32_sdwa v6, v10, v6 dst_sel:DWORD dst_unused:UNUSED_PAD src0_sel:DWORD src1_sel:WORD_1
	v_pk_mul_f32 v[2:3], v[2:3], v[18:19] op_sel_hi:[1,0]
	global_store_dwordx2 v[36:37], v[6:7], off offset:3072 sc1
	v_pk_mul_f32 v[2:3], v[68:69], v[2:3]
	v_pk_mul_f32 v[6:7], v[8:9], v[18:19] op_sel_hi:[1,0]
	s_cmpk_gt_i32 s0, 0x43ff
	v_pk_mul_f32 v[4:5], v[4:5], v[6:7]
	v_and_b32_sdwa v6, v3, v106 dst_sel:DWORD dst_unused:UNUSED_PAD src0_sel:WORD_1 src1_sel:DWORD
	v_and_b32_sdwa v7, v2, v106 dst_sel:DWORD dst_unused:UNUSED_PAD src0_sel:WORD_1 src1_sel:DWORD
	v_add3_u32 v2, v2, v7, s18
	v_add3_u32 v3, v3, v6, s18
	v_and_b32_sdwa v6, v5, v106 dst_sel:DWORD dst_unused:UNUSED_PAD src0_sel:WORD_1 src1_sel:DWORD
	v_and_b32_sdwa v7, v4, v106 dst_sel:DWORD dst_unused:UNUSED_PAD src0_sel:WORD_1 src1_sel:DWORD
	v_add3_u32 v5, v5, v6, s18
	v_add3_u32 v4, v4, v7, s18
	v_and_b32_e32 v5, 0xffff0000, v5
	v_and_b32_e32 v4, 0xffff0000, v4
	v_or_b32_sdwa v3, v5, v3 dst_sel:DWORD dst_unused:UNUSED_PAD src0_sel:DWORD src1_sel:WORD_1
	v_or_b32_sdwa v2, v4, v2 dst_sel:DWORD dst_unused:UNUSED_PAD src0_sel:DWORD src1_sel:WORD_1
	v_lshl_add_u64 v[92:93], v[92:93], 0, s[10:11]
	global_store_dwordx2 v[96:97], v[74:75], off offset:1536 sc1
	global_store_dwordx2 v[36:37], v[2:3], off offset:3584 sc1
	s_cbranch_scc1 .LBB0_22
.LBB0_18:
	s_cmpk_gt_i32 s0, 0x3fff
	s_mov_b64 s[14:15], -1
	s_cbranch_scc0 .LBB0_20
	s_add_i32 s12, s0, 0xffffc000
	s_lshl_b64 s[14:15], s[12:13], 12
	v_lshl_add_u64 v[6:7], v[82:83], 0, s[14:15]
	v_add_co_u32_e32 v22, vcc, 0x1000, v6
	global_load_dwordx4 v[78:81], v[6:7], off nt
	global_load_dwordx4 v[74:77], v[6:7], off offset:1024 nt
	global_load_dwordx4 v[2:5], v[6:7], off offset:3072 nt
	global_load_dwordx4 v[66:69], v[6:7], off offset:2048 nt
	v_addc_co_u32_e32 v23, vcc, 0, v7, vcc
	v_add_co_u32_e32 v24, vcc, 0x2000, v6
	global_load_dwordx4 v[50:53], v[22:23], off nt
	global_load_dwordx4 v[42:45], v[22:23], off offset:1024 nt
	v_addc_co_u32_e32 v25, vcc, 0, v7, vcc
	global_load_dwordx4 v[34:37], v[24:25], off nt
	global_load_dwordx4 v[30:33], v[24:25], off offset:1024 nt
	v_add_co_u32_e32 v10, vcc, 0x3000, v6
	s_lshl_b64 s[14:15], s[12:13], 11
	s_nop 0
	v_addc_co_u32_e32 v11, vcc, 0, v7, vcc
	global_load_dwordx4 v[18:21], v[10:11], off nt
	global_load_dwordx4 v[14:17], v[10:11], off offset:1024 nt
	global_load_dwordx4 v[6:9], v[10:11], off offset:3072 nt
	s_nop 0
	global_load_dwordx4 v[10:13], v[10:11], off offset:2048 nt
	s_nop 0
	global_load_dwordx4 v[46:49], v[22:23], off offset:2048 nt
	global_load_dwordx4 v[38:41], v[22:23], off offset:3072 nt
	global_load_dwordx4 v[26:29], v[24:25], off offset:2048 nt
	s_nop 0
	global_load_dwordx4 v[22:25], v[24:25], off offset:3072 nt
	v_cmp_lt_i32_e32 vcc, v100, v99
	s_waitcnt vmcnt(15)
	v_pk_mul_f32 v[54:55], v[80:81], v[80:81]
	v_pk_mul_f32 v[56:57], v[78:79], v[78:79]
	s_waitcnt vmcnt(14)
	v_pk_mul_f32 v[58:59], v[76:77], v[76:77]
	v_pk_mul_f32 v[60:61], v[74:75], v[74:75]
	s_waitcnt vmcnt(13)
	v_mul_f32_e32 v65, v4, v4
	s_waitcnt vmcnt(12)
	v_mul_f32_e32 v62, v67, v67
	v_mul_f32_e32 v64, v69, v69
	v_pk_mov_b32 v[70:71], v[56:57], v[54:55] op_sel:[1,0]
	v_mov_b32_e32 v57, v55
	v_pk_mov_b32 v[54:55], v[60:61], v[58:59] op_sel:[1,0]
	v_mov_b32_e32 v61, v59
	v_mul_f32_e32 v72, v5, v5
	v_pk_fma_f32 v[58:59], v[66:67], v[66:67], v[62:63] op_sel_hi:[1,1,0]
	v_pk_fma_f32 v[62:63], v[68:69], v[68:69], v[64:65] op_sel_hi:[1,1,0]
	v_pk_add_f32 v[56:57], v[70:71], v[56:57]
	v_pk_add_f32 v[54:55], v[54:55], v[60:61]
	v_mul_f32_e32 v107, v2, v2
	v_mul_f32_e32 v108, v3, v3
	v_mov_b32_e32 v59, v65
	v_mov_b32_e32 v63, v72
	s_waitcnt vmcnt(11)
	v_mov_b32_e32 v64, v51
	v_mov_b32_e32 v72, v53
	v_pk_add_f32 v[56:57], v[56:57], v[56:57] op_sel:[0,1] op_sel_hi:[1,0]
	v_pk_add_f32 v[54:55], v[54:55], v[54:55] op_sel:[0,1] op_sel_hi:[1,0]
	s_waitcnt vmcnt(9)
	v_mov_b32_e32 v65, v35
	v_mov_b32_e32 v73, v37
	v_pk_add_f32 v[58:59], v[58:59], v[62:63]
	v_mov_b32_e32 v57, v107
	v_mov_b32_e32 v55, v108
	v_pk_mul_f32 v[62:63], v[64:65], v[64:65]
	v_pk_mul_f32 v[64:65], v[72:73], v[72:73]
	s_waitcnt vmcnt(7)
	v_pk_mul_f32 v[72:73], v[20:21], v[20:21]
	v_pk_mul_f32 v[108:109], v[18:19], v[18:19]
	s_waitcnt vmcnt(6)
	v_pk_mul_f32 v[110:111], v[16:17], v[16:17]
	v_pk_mul_f32 v[112:113], v[14:15], v[14:15]
	v_pk_add_f32 v[54:55], v[56:57], v[54:55]
	v_pk_mov_b32 v[56:57], v[108:109], v[72:73] op_sel:[1,0]
	v_mov_b32_e32 v109, v73
	v_pk_mov_b32 v[72:73], v[112:113], v[110:111] op_sel:[1,0]
	v_mov_b32_e32 v113, v111
	v_pk_add_f32 v[54:55], v[54:55], v[58:59]
	v_pk_add_f32 v[56:57], v[56:57], v[108:109]
	v_pk_add_f32 v[58:59], v[72:73], v[112:113]
	v_add_f32_e32 v72, v54, v55
	v_pk_add_f32 v[54:55], v[56:57], v[56:57] op_sel:[0,1] op_sel_hi:[1,0]
	v_pk_add_f32 v[56:57], v[58:59], v[58:59] op_sel:[0,1] op_sel_hi:[1,0]
	s_waitcnt vmcnt(4)
	v_mul_f32_e32 v58, v13, v13
	v_mul_f32_e32 v107, v6, v6
	v_mul_f32_e32 v114, v7, v7
	v_pk_fma_f32 v[58:59], v[12:13], v[12:13], v[58:59] op_sel_hi:[1,1,0]
	v_mov_b32_e32 v55, v107
	v_mov_b32_e32 v57, v114
	v_cndmask_b32_e32 v59, v98, v100, vcc
	v_pk_add_f32 v[54:55], v[54:55], v[56:57]
	v_mul_f32_e32 v56, v11, v11
	v_lshlrev_b32_e32 v73, 2, v59
	v_mul_f32_e32 v115, v8, v8
	v_mul_f32_e32 v116, v9, v9
	v_pk_fma_f32 v[56:57], v[10:11], v[10:11], v[56:57] op_sel_hi:[1,1,0]
	ds_bpermute_b32 v107, v73, v72
	v_mov_b32_e32 v57, v115
	v_mov_b32_e32 v59, v116
	v_pk_add_f32 v[56:57], v[56:57], v[58:59]
	v_cmp_lt_i32_e32 vcc, v101, v99
	v_pk_add_f32 v[54:55], v[54:55], v[56:57]
	s_waitcnt lgkmcnt(0)
	v_add_f32_e32 v59, v72, v107
	v_add_f32_e32 v58, v54, v55
	v_cndmask_b32_e32 v54, v98, v101, vcc
	ds_bpermute_b32 v72, v73, v58
	v_lshlrev_b32_e32 v107, 2, v54
	ds_bpermute_b32 v108, v107, v59
	v_cmp_lt_i32_e32 vcc, v102, v99
	v_mov_b32_e32 v96, v43
	v_mov_b32_e32 v97, v31
	s_waitcnt lgkmcnt(1)
	v_add_f32_e32 v72, v58, v72
	v_cndmask_b32_e32 v58, v98, v102, vcc
	v_pk_mul_f32 v[54:55], v[96:97], v[96:97]
	s_waitcnt lgkmcnt(0)
	v_add_f32_e32 v96, v59, v108
	v_lshlrev_b32_e32 v108, 2, v58
	v_mov_b32_e32 v58, v45
	v_mov_b32_e32 v59, v33
	v_mov_b32_e32 v60, v50
	v_mov_b32_e32 v70, v52
	v_mov_b32_e32 v94, v42
	v_mov_b32_e32 v61, v34
	v_mov_b32_e32 v71, v36
	v_mov_b32_e32 v95, v30
	v_mov_b32_e32 v56, v44
	v_mov_b32_e32 v57, v32
	v_pk_mul_f32 v[58:59], v[58:59], v[58:59]
	v_pk_fma_f32 v[60:61], v[60:61], v[60:61], v[62:63]
	v_pk_fma_f32 v[62:63], v[70:71], v[70:71], v[64:65]
	v_pk_fma_f32 v[54:55], v[94:95], v[94:95], v[54:55]
	v_pk_fma_f32 v[56:57], v[56:57], v[56:57], v[58:59]
	v_pk_add_f32 v[60:61], v[60:61], v[62:63]
	v_pk_add_f32 v[54:55], v[54:55], v[56:57]
	s_waitcnt vmcnt(3)
	v_mov_b32_e32 v56, v47
	s_waitcnt vmcnt(1)
	v_mov_b32_e32 v57, v27
	v_mov_b32_e32 v64, v49
	v_mov_b32_e32 v65, v29
	v_pk_add_f32 v[58:59], v[60:61], v[54:55]
	v_mov_b32_e32 v54, v46
	v_mov_b32_e32 v55, v26
	v_pk_mul_f32 v[56:57], v[56:57], v[56:57]
	v_mov_b32_e32 v62, v48
	v_mov_b32_e32 v63, v28
	v_pk_mul_f32 v[64:65], v[64:65], v[64:65]
	v_pk_fma_f32 v[60:61], v[54:55], v[54:55], v[56:57]
	v_pk_fma_f32 v[62:63], v[62:63], v[62:63], v[64:65]
	v_mov_b32_e32 v64, v41
	v_pk_add_f32 v[60:61], v[60:61], v[62:63]
	v_mov_b32_e32 v62, v39
	s_waitcnt vmcnt(0)
	v_mov_b32_e32 v63, v23
	v_pk_add_f32 v[58:59], v[58:59], v[60:61]
	v_mov_b32_e32 v60, v38
	v_mov_b32_e32 v61, v22
	v_pk_mul_f32 v[62:63], v[62:63], v[62:63]
	v_mov_b32_e32 v65, v25
	v_pk_fma_f32 v[60:61], v[60:61], v[60:61], v[62:63]
	v_mov_b32_e32 v62, v40
	v_mov_b32_e32 v63, v24
	v_pk_mul_f32 v[64:65], v[64:65], v[64:65]
	ds_bpermute_b32 v109, v108, v96
	v_pk_fma_f32 v[62:63], v[62:63], v[62:63], v[64:65]
	ds_bpermute_b32 v97, v107, v72
	v_pk_add_f32 v[60:61], v[60:61], v[62:63]
	v_cmp_lt_i32_e32 vcc, v103, v99
	v_pk_add_f32 v[62:63], v[58:59], v[60:61]
	ds_bpermute_b32 v64, v73, v62
	ds_bpermute_b32 v65, v73, v63
	v_cndmask_b32_e32 v70, v98, v103, vcc
	s_waitcnt lgkmcnt(3)
	v_add_f32_e32 v96, v96, v109
	v_lshlrev_b32_e32 v73, 2, v70
	s_waitcnt lgkmcnt(2)
	v_add_f32_e32 v72, v72, v97
	s_waitcnt lgkmcnt(0)
	v_pk_add_f32 v[62:63], v[62:63], v[64:65]
	ds_bpermute_b32 v64, v107, v62
	ds_bpermute_b32 v65, v107, v63
	ds_bpermute_b32 v70, v73, v96
	ds_bpermute_b32 v97, v108, v72
	global_load_dwordx4 v[54:57], v[84:85], off
	global_load_dwordx4 v[58:61], v[84:85], off offset:1024
	s_waitcnt lgkmcnt(2)
	v_pk_add_f32 v[62:63], v[62:63], v[64:65]
	ds_bpermute_b32 v64, v108, v62
	ds_bpermute_b32 v65, v108, v63
	v_cmp_lt_i32_e32 vcc, v104, v99
	s_waitcnt lgkmcnt(3)
	v_add_f32_e32 v95, v96, v70
	s_waitcnt lgkmcnt(2)
	v_add_f32_e32 v94, v72, v97
	v_cndmask_b32_e32 v70, v98, v104, vcc
	v_lshlrev_b32_e32 v97, 2, v70
	s_waitcnt lgkmcnt(0)
	v_pk_add_f32 v[70:71], v[62:63], v[64:65]
	ds_bpermute_b32 v96, v73, v94
	ds_bpermute_b32 v72, v73, v70
	ds_bpermute_b32 v73, v73, v71
	ds_bpermute_b32 v107, v97, v95
	v_cmp_lt_i32_e32 vcc, v105, v99
	s_waitcnt lgkmcnt(3)
	v_add_f32_e32 v94, v94, v96
	ds_bpermute_b32 v96, v97, v94
	s_waitcnt lgkmcnt(2)
	v_pk_add_f32 v[70:71], v[70:71], v[72:73]
	ds_bpermute_b32 v72, v97, v70
	ds_bpermute_b32 v73, v97, v71
	v_cndmask_b32_e32 v97, v98, v105, vcc
	s_waitcnt lgkmcnt(3)
	v_add_f32_e32 v95, v95, v107
	global_load_dwordx4 v[62:65], v[84:85], off offset:2048
	v_lshlrev_b32_e32 v97, 2, v97
	s_waitcnt lgkmcnt(0)
	v_pk_add_f32 v[70:71], v[70:71], v[72:73]
	ds_bpermute_b32 v107, v97, v95
	ds_bpermute_b32 v72, v97, v70
	ds_bpermute_b32 v73, v97, v71
	v_add_f32_e32 v96, v94, v96
	v_mov_b32_e32 v110, v78
	s_waitcnt lgkmcnt(2)
	v_add_f32_e32 v107, v95, v107
	v_fmamk_f32 v107, v107, 0x3a800000, v1
	s_waitcnt lgkmcnt(0)
	v_pk_add_f32 v[94:95], v[70:71], v[72:73]
	global_load_dwordx4 v[70:73], v[84:85], off offset:3072
	v_mul_f32_e32 v108, 0x4b800000, v107
	v_cmp_gt_f32_e32 vcc, s7, v107
	v_mov_b32_e32 v111, v80
	v_mov_b32_e32 v80, v79
	v_cndmask_b32_e32 v107, v107, v108, vcc
	v_rsq_f32_e32 v108, v107
	ds_bpermute_b32 v97, v97, v96
	v_mul_f32_e32 v109, 0x45800000, v108
	v_cndmask_b32_e32 v108, v108, v109, vcc
	v_pk_mul_f32 v[110:111], v[110:111], v[108:109] op_sel_hi:[1,0]
	v_pk_mul_f32 v[78:79], v[80:81], v[108:109] op_sel_hi:[1,0]
	s_waitcnt lgkmcnt(0)
	v_add_f32_e32 v107, v96, v97
	v_lshl_add_u64 v[96:97], v[86:87], 0, s[14:15]
	s_mov_b64 s[14:15], 0
	s_waitcnt vmcnt(3)
	v_mov_b32_e32 v112, v54
	v_mov_b32_e32 v113, v56
	v_pk_mul_f32 v[110:111], v[112:113], v[110:111]
	v_mov_b32_e32 v80, v55
	v_mov_b32_e32 v81, v57
	v_pk_mul_f32 v[78:79], v[80:81], v[78:79]
	v_and_b32_sdwa v81, v110, v106 dst_sel:DWORD dst_unused:UNUSED_PAD src0_sel:WORD_1 src1_sel:DWORD
	v_add3_u32 v81, v110, v81, s18
	v_and_b32_sdwa v109, v79, v106 dst_sel:DWORD dst_unused:UNUSED_PAD src0_sel:WORD_1 src1_sel:DWORD
	v_and_b32_sdwa v110, v78, v106 dst_sel:DWORD dst_unused:UNUSED_PAD src0_sel:WORD_1 src1_sel:DWORD
	v_and_b32_sdwa v80, v111, v106 dst_sel:DWORD dst_unused:UNUSED_PAD src0_sel:WORD_1 src1_sel:DWORD
	v_add3_u32 v79, v79, v109, s18
	v_add3_u32 v78, v78, v110, s18
	v_add3_u32 v80, v111, v80, s18
	v_and_b32_e32 v79, 0xffff0000, v79
	v_and_b32_e32 v78, 0xffff0000, v78
	v_or_b32_sdwa v79, v79, v80 dst_sel:DWORD dst_unused:UNUSED_PAD src0_sel:DWORD src1_sel:WORD_1
	v_or_b32_sdwa v78, v78, v81 dst_sel:DWORD dst_unused:UNUSED_PAD src0_sel:DWORD src1_sel:WORD_1
	global_store_dwordx2 v[96:97], v[78:79], off sc1
	v_mov_b32_e32 v78, v74
	v_mov_b32_e32 v79, v76
	v_pk_mul_f32 v[78:79], v[78:79], v[108:109] op_sel_hi:[1,0]
	s_waitcnt vmcnt(3)
	v_mov_b32_e32 v80, v58
	v_mov_b32_e32 v81, v60
	v_mov_b32_e32 v76, v75
	v_pk_mul_f32 v[78:79], v[80:81], v[78:79]
	v_pk_mul_f32 v[74:75], v[76:77], v[108:109] op_sel_hi:[1,0]
	v_mov_b32_e32 v76, v59
	v_mov_b32_e32 v77, v61
	v_pk_mul_f32 v[74:75], v[76:77], v[74:75]
	v_and_b32_sdwa v76, v79, v106 dst_sel:DWORD dst_unused:UNUSED_PAD src0_sel:WORD_1 src1_sel:DWORD
	v_and_b32_sdwa v77, v78, v106 dst_sel:DWORD dst_unused:UNUSED_PAD src0_sel:WORD_1 src1_sel:DWORD
	v_add3_u32 v77, v78, v77, s18
	v_add3_u32 v76, v79, v76, s18
	v_and_b32_sdwa v78, v75, v106 dst_sel:DWORD dst_unused:UNUSED_PAD src0_sel:WORD_1 src1_sel:DWORD
	v_and_b32_sdwa v79, v74, v106 dst_sel:DWORD dst_unused:UNUSED_PAD src0_sel:WORD_1 src1_sel:DWORD
	v_add3_u32 v75, v75, v78, s18
	v_add3_u32 v74, v74, v79, s18
	v_and_b32_e32 v75, 0xffff0000, v75
	v_and_b32_e32 v74, 0xffff0000, v74
	v_or_b32_sdwa v75, v75, v76 dst_sel:DWORD dst_unused:UNUSED_PAD src0_sel:DWORD src1_sel:WORD_1
	v_or_b32_sdwa v74, v74, v77 dst_sel:DWORD dst_unused:UNUSED_PAD src0_sel:DWORD src1_sel:WORD_1
	global_store_dwordx2 v[96:97], v[74:75], off offset:512 sc1
	v_mov_b32_e32 v74, v66
	v_mov_b32_e32 v75, v68
	v_pk_mul_f32 v[74:75], v[74:75], v[108:109] op_sel_hi:[1,0]
	s_waitcnt vmcnt(3)
	v_mov_b32_e32 v76, v62
	v_mov_b32_e32 v77, v64
	v_mov_b32_e32 v68, v67
	v_pk_mul_f32 v[74:75], v[76:77], v[74:75]
	v_pk_mul_f32 v[66:67], v[68:69], v[108:109] op_sel_hi:[1,0]
	v_mov_b32_e32 v68, v63
	v_mov_b32_e32 v69, v65
	v_pk_mul_f32 v[66:67], v[68:69], v[66:67]
	v_and_b32_sdwa v68, v75, v106 dst_sel:DWORD dst_unused:UNUSED_PAD src0_sel:WORD_1 src1_sel:DWORD
	v_and_b32_sdwa v69, v74, v106 dst_sel:DWORD dst_unused:UNUSED_PAD src0_sel:WORD_1 src1_sel:DWORD
	v_add3_u32 v69, v74, v69, s18
	v_add3_u32 v68, v75, v68, s18
	v_and_b32_sdwa v74, v67, v106 dst_sel:DWORD dst_unused:UNUSED_PAD src0_sel:WORD_1 src1_sel:DWORD
	v_and_b32_sdwa v75, v66, v106 dst_sel:DWORD dst_unused:UNUSED_PAD src0_sel:WORD_1 src1_sel:DWORD
	v_add3_u32 v67, v67, v74, s18
	v_add3_u32 v66, v66, v75, s18
	v_and_b32_e32 v67, 0xffff0000, v67
	v_and_b32_e32 v66, 0xffff0000, v66
	v_pk_mul_f32 v[2:3], v[2:3], v[108:109] op_sel_hi:[1,0]
	v_or_b32_sdwa v67, v67, v68 dst_sel:DWORD dst_unused:UNUSED_PAD src0_sel:DWORD src1_sel:WORD_1
	v_or_b32_sdwa v66, v66, v69 dst_sel:DWORD dst_unused:UNUSED_PAD src0_sel:DWORD src1_sel:WORD_1
	s_waitcnt vmcnt(2)
	v_pk_mul_f32 v[2:3], v[70:71], v[2:3]
	global_store_dwordx2 v[96:97], v[66:67], off offset:1024 sc1
	v_and_b32_sdwa v67, v2, v106 dst_sel:DWORD dst_unused:UNUSED_PAD src0_sel:WORD_1 src1_sel:DWORD
	v_and_b32_sdwa v66, v3, v106 dst_sel:DWORD dst_unused:UNUSED_PAD src0_sel:WORD_1 src1_sel:DWORD
	v_add3_u32 v2, v2, v67, s18
	v_add3_u32 v3, v3, v66, s18
	v_lshrrev_b32_e32 v2, 16, v2
	v_and_or_b32 v74, v3, s19, v2
	v_mul_f32_e32 v109, v4, v108
	v_pk_mov_b32 v[2:3], v[4:5], v[72:73] op_sel:[1,0]
	v_mov_b32_e32 v69, v72
	v_pk_mul_f32 v[76:77], v[2:3], v[108:109]
	v_mov_b32_e32 v3, v8
	v_mov_b32_e32 v2, v6
	v_mov_b32_e32 v8, v7
	v_mov_b32_e32 v7, v12
	v_mov_b32_e32 v6, v10
	v_mov_b32_e32 v12, v11
	v_mov_b32_e32 v11, v16
	v_mov_b32_e32 v10, v14
	v_mov_b32_e32 v16, v15
	v_mov_b32_e32 v15, v20
	v_mov_b32_e32 v14, v18
	v_mov_b32_e32 v20, v19
	v_mov_b32_e32 v19, v24
	v_mov_b32_e32 v18, v22
	v_mov_b32_e32 v24, v23
	v_mov_b32_e32 v23, v28
	v_mov_b32_e32 v22, v26
	v_mov_b32_e32 v28, v27
	v_mov_b32_e32 v27, v32
	v_mov_b32_e32 v26, v30
	v_mov_b32_e32 v32, v31
	v_mov_b32_e32 v31, v36
	v_mov_b32_e32 v30, v34
	v_mov_b32_e32 v36, v35
	v_mov_b32_e32 v35, v40
	v_mov_b32_e32 v34, v38
	v_mov_b32_e32 v68, v70
	v_mov_b32_e32 v40, v39
	v_mov_b32_e32 v39, v48
	v_mov_b32_e32 v38, v46
	v_mov_b32_e32 v67, v64
	v_mov_b32_e32 v66, v62
	v_mov_b32_e32 v48, v47
	v_mov_b32_e32 v64, v63
	v_mov_b32_e32 v47, v44
	v_mov_b32_e32 v46, v42
	v_mov_b32_e32 v63, v60
	v_mov_b32_e32 v62, v58
	v_mov_b32_e32 v44, v43
	v_mov_b32_e32 v60, v59
	v_mov_b32_e32 v43, v52
	v_mov_b32_e32 v42, v50
	v_mov_b32_e32 v59, v56
	v_mov_b32_e32 v58, v54
	v_mov_b32_e32 v52, v51
	v_mov_b32_e32 v56, v55
	v_mov_b32_e32 v4, v71
.LBB0_20:
	s_andn2_b64 vcc, exec, s[14:15]
	s_cbranch_vccnz .LBB0_17
	global_load_dwordx4 v[14:17], v[92:93], off offset:-3072 nt
	global_load_dwordx4 v[10:13], v[92:93], off offset:-2048 nt
	global_load_dwordx4 v[2:5], v[92:93], off nt
	v_add_co_u32_e32 v6, vcc, 0xffffd000, v92
	s_waitcnt vmcnt(2)
	v_pk_mul_f32 v[58:59], v[16:17], v[16:17]
	v_addc_co_u32_e32 v7, vcc, -1, v93, vcc
	global_load_dwordx4 v[78:81], v[6:7], off offset:-3072 nt
	global_load_dwordx4 v[74:77], v[6:7], off offset:-2048 nt
	global_load_dwordx4 v[50:53], v[6:7], off nt
	global_load_dwordx4 v[54:57], v[6:7], off offset:-1024 nt
	v_add_co_u32_e32 v18, vcc, 0xffffe000, v92
	v_pk_mul_f32 v[60:61], v[14:15], v[14:15]
	s_nop 0
	v_addc_co_u32_e32 v19, vcc, -1, v93, vcc
	v_add_co_u32_e32 v20, vcc, 0xfffff000, v92
	global_load_dwordx4 v[42:45], v[18:19], off offset:-3072 nt
	global_load_dwordx4 v[46:49], v[18:19], off offset:-2048 nt
	v_addc_co_u32_e32 v21, vcc, -1, v93, vcc
	global_load_dwordx4 v[30:33], v[20:21], off offset:-3072 nt
	global_load_dwordx4 v[26:29], v[20:21], off offset:-2048 nt
	global_load_dwordx4 v[6:9], v[92:93], off offset:-1024 nt
	global_load_dwordx4 v[38:41], v[18:19], off offset:-1024 nt
	global_load_dwordx4 v[34:37], v[18:19], off nt
	global_load_dwordx4 v[22:25], v[20:21], off offset:-1024 nt
	s_nop 0
	global_load_dwordx4 v[18:21], v[92:93], off offset:-4096 nt
	s_waitcnt vmcnt(14)
	v_pk_mul_f32 v[62:63], v[12:13], v[12:13]
	v_pk_mul_f32 v[64:65], v[10:11], v[10:11]
	v_pk_mov_b32 v[66:67], v[60:61], v[58:59] op_sel:[1,0]
	v_mov_b32_e32 v61, v59
	v_pk_mov_b32 v[58:59], v[64:65], v[62:63] op_sel:[1,0]
	v_mov_b32_e32 v65, v63
	v_pk_add_f32 v[58:59], v[58:59], v[64:65]
	v_pk_add_f32 v[60:61], v[66:67], v[60:61]
	s_waitcnt vmcnt(13)
	v_mul_f32_e32 v107, v2, v2
	v_mul_f32_e32 v116, v3, v3
	v_pk_add_f32 v[60:61], v[60:61], v[60:61] op_sel:[0,1] op_sel_hi:[1,0]
	v_pk_add_f32 v[58:59], v[58:59], v[58:59] op_sel:[0,1] op_sel_hi:[1,0]
	v_cmp_lt_i32_e32 vcc, v100, v99
	v_mov_b32_e32 v61, v107
	v_mov_b32_e32 v59, v116
	v_pk_add_f32 v[58:59], v[60:61], v[58:59]
	v_mul_f32_e32 v117, v4, v4
	v_mul_f32_e32 v118, v5, v5
	s_waitcnt vmcnt(12)
	v_pk_mul_f32 v[62:63], v[80:81], v[80:81]
	v_pk_mul_f32 v[68:69], v[78:79], v[78:79]
	s_waitcnt vmcnt(11)
	v_pk_mul_f32 v[70:71], v[76:77], v[76:77]
	v_pk_mul_f32 v[72:73], v[74:75], v[74:75]
	v_pk_mov_b32 v[64:65], v[68:69], v[62:63] op_sel:[1,0]
	v_mov_b32_e32 v69, v63
	v_pk_mov_b32 v[62:63], v[72:73], v[70:71] op_sel:[1,0]
	v_mov_b32_e32 v73, v71
	s_waitcnt vmcnt(10)
	v_mul_f32_e32 v95, v52, v52
	v_mul_f32_e32 v97, v53, v53
	s_waitcnt vmcnt(9)
	v_mul_f32_e32 v94, v55, v55
	v_mul_f32_e32 v96, v57, v57
	v_pk_add_f32 v[64:65], v[64:65], v[68:69]
	v_pk_add_f32 v[62:63], v[62:63], v[72:73]
	v_mul_f32_e32 v119, v50, v50
	v_mul_f32_e32 v120, v51, v51
	v_pk_fma_f32 v[66:67], v[54:55], v[54:55], v[94:95] op_sel_hi:[1,1,0]
	v_pk_fma_f32 v[70:71], v[56:57], v[56:57], v[96:97] op_sel_hi:[1,1,0]
	v_pk_add_f32 v[64:65], v[64:65], v[64:65] op_sel:[0,1] op_sel_hi:[1,0]
	v_pk_add_f32 v[62:63], v[62:63], v[62:63] op_sel:[0,1] op_sel_hi:[1,0]
	v_mov_b32_e32 v67, v95
	v_mov_b32_e32 v71, v97
	v_mov_b32_e32 v65, v119
	v_mov_b32_e32 v63, v120
	v_pk_add_f32 v[66:67], v[66:67], v[70:71]
	v_pk_add_f32 v[62:63], v[64:65], v[62:63]
	s_waitcnt vmcnt(4)
	v_mul_f32_e32 v60, v7, v7
	v_pk_add_f32 v[62:63], v[62:63], v[66:67]
	v_pk_fma_f32 v[60:61], v[6:7], v[6:7], v[60:61] op_sel_hi:[1,1,0]
	v_add_f32_e32 v64, v62, v63
	v_mul_f32_e32 v62, v9, v9
	v_pk_fma_f32 v[62:63], v[8:9], v[8:9], v[62:63] op_sel_hi:[1,1,0]
	v_mov_b32_e32 v61, v117
	v_cndmask_b32_e32 v63, v98, v100, vcc
	v_lshlrev_b32_e32 v72, 2, v63
	ds_bpermute_b32 v65, v72, v64
	v_mov_b32_e32 v63, v118
	v_pk_add_f32 v[60:61], v[60:61], v[62:63]
	v_cmp_lt_i32_e32 vcc, v101, v99
	v_pk_add_f32 v[58:59], v[58:59], v[60:61]
	s_waitcnt lgkmcnt(0)
	v_add_f32_e32 v63, v64, v65
	v_add_f32_e32 v62, v58, v59
	v_cndmask_b32_e32 v58, v98, v101, vcc
	ds_bpermute_b32 v64, v72, v62
	v_lshlrev_b32_e32 v73, 2, v58
	ds_bpermute_b32 v65, v73, v63
	v_cmp_lt_i32_e32 vcc, v102, v99
	v_mov_b32_e32 v96, v43
	v_mov_b32_e32 v97, v31
	s_waitcnt lgkmcnt(1)
	v_add_f32_e32 v64, v62, v64
	v_cndmask_b32_e32 v62, v98, v102, vcc
	v_pk_mul_f32 v[68:69], v[96:97], v[96:97]
	s_waitcnt lgkmcnt(0)
	v_add_f32_e32 v65, v63, v65
	ds_bpermute_b32 v66, v73, v64
	v_lshlrev_b32_e32 v96, 2, v62
	ds_bpermute_b32 v67, v96, v65
	v_mov_b32_e32 v110, v45
	v_mov_b32_e32 v114, v47
	v_mov_b32_e32 v111, v33
	v_mov_b32_e32 v115, v27
	v_mov_b32_e32 v62, v49
	v_mov_b32_e32 v63, v29
	v_cmp_lt_i32_e32 vcc, v103, v99
	v_mov_b32_e32 v94, v42
	v_mov_b32_e32 v108, v44
	v_mov_b32_e32 v112, v46
	v_mov_b32_e32 v95, v30
	v_mov_b32_e32 v109, v32
	v_mov_b32_e32 v113, v26
	v_pk_mul_f32 v[70:71], v[110:111], v[110:111]
	v_pk_mul_f32 v[58:59], v[114:115], v[114:115]
	v_mov_b32_e32 v60, v48
	v_mov_b32_e32 v61, v28
	v_pk_mul_f32 v[62:63], v[62:63], v[62:63]
	s_waitcnt lgkmcnt(1)
	v_add_f32_e32 v97, v64, v66
	v_cndmask_b32_e32 v64, v98, v103, vcc
	s_waitcnt lgkmcnt(0)
	v_add_f32_e32 v107, v65, v67
	v_lshlrev_b32_e32 v111, 2, v64
	v_pk_fma_f32 v[64:65], v[94:95], v[94:95], v[68:69]
	v_pk_fma_f32 v[66:67], v[108:109], v[108:109], v[70:71]
	v_pk_fma_f32 v[58:59], v[112:113], v[112:113], v[58:59]
	v_pk_fma_f32 v[60:61], v[60:61], v[60:61], v[62:63]
	v_pk_add_f32 v[64:65], v[64:65], v[66:67]
	v_pk_add_f32 v[58:59], v[58:59], v[60:61]
	s_waitcnt vmcnt(3)
	v_mov_b32_e32 v66, v39
	s_waitcnt vmcnt(1)
	v_mov_b32_e32 v67, v23
	v_pk_add_f32 v[62:63], v[64:65], v[58:59]
	v_mov_b32_e32 v64, v38
	v_mov_b32_e32 v65, v22
	v_pk_mul_f32 v[66:67], v[66:67], v[66:67]
	v_mov_b32_e32 v68, v41
	v_mov_b32_e32 v69, v25
	v_pk_fma_f32 v[64:65], v[64:65], v[64:65], v[66:67]
	v_mov_b32_e32 v66, v40
	v_mov_b32_e32 v67, v24
	v_pk_mul_f32 v[68:69], v[68:69], v[68:69]
	ds_bpermute_b32 v110, v96, v97
	v_pk_fma_f32 v[66:67], v[66:67], v[66:67], v[68:69]
	ds_bpermute_b32 v114, v111, v107
	v_pk_add_f32 v[64:65], v[64:65], v[66:67]
	global_load_dwordx4 v[58:61], v[88:89], off
	v_pk_add_f32 v[66:67], v[62:63], v[64:65]
	v_mov_b32_e32 v64, v35
	s_waitcnt vmcnt(1)
	v_mov_b32_e32 v65, v19
	v_mov_b32_e32 v62, v34
	v_mov_b32_e32 v63, v18
	v_pk_mul_f32 v[64:65], v[64:65], v[64:65]
	v_cmp_lt_i32_e32 vcc, v104, v99
	v_pk_fma_f32 v[68:69], v[62:63], v[62:63], v[64:65]
	v_mov_b32_e32 v64, v37
	v_mov_b32_e32 v65, v21
	v_mov_b32_e32 v62, v36
	v_mov_b32_e32 v63, v20
	v_pk_mul_f32 v[64:65], v[64:65], v[64:65]
	s_nop 0
	v_pk_fma_f32 v[70:71], v[62:63], v[62:63], v[64:65]
	global_load_dwordx4 v[62:65], v[88:89], off offset:1024
	v_pk_add_f32 v[68:69], v[68:69], v[70:71]
	s_waitcnt lgkmcnt(1)
	v_add_f32_e32 v70, v97, v110
	v_pk_add_f32 v[66:67], v[66:67], v[68:69]
	ds_bpermute_b32 v68, v72, v66
	ds_bpermute_b32 v69, v72, v67
	s_waitcnt lgkmcnt(2)
	v_add_f32_e32 v71, v107, v114
	ds_bpermute_b32 v72, v111, v70
	s_waitcnt lgkmcnt(1)
	v_pk_add_f32 v[66:67], v[66:67], v[68:69]
	ds_bpermute_b32 v68, v73, v66
	ds_bpermute_b32 v69, v73, v67
	v_cndmask_b32_e32 v73, v98, v104, vcc
	v_lshlrev_b32_e32 v94, 2, v73
	ds_bpermute_b32 v73, v94, v71
	s_waitcnt lgkmcnt(3)
	v_add_f32_e32 v95, v70, v72
	s_waitcnt lgkmcnt(1)
	v_pk_add_f32 v[66:67], v[66:67], v[68:69]
	ds_bpermute_b32 v68, v96, v66
	ds_bpermute_b32 v69, v96, v67
	s_waitcnt lgkmcnt(2)
	v_add_f32_e32 v96, v71, v73
	ds_bpermute_b32 v97, v94, v95
	v_cmp_lt_i32_e32 vcc, v105, v99
	s_waitcnt lgkmcnt(1)
	v_pk_add_f32 v[70:71], v[66:67], v[68:69]
	ds_bpermute_b32 v72, v111, v70
	ds_bpermute_b32 v73, v111, v71
	global_load_dwordx4 v[66:69], v[88:89], off offset:2048
	s_waitcnt lgkmcnt(2)
	v_add_f32_e32 v109, v95, v97
	v_cndmask_b32_e32 v107, v98, v105, vcc
	v_lshlrev_b32_e32 v107, 2, v107
	s_waitcnt lgkmcnt(0)
	v_pk_add_f32 v[70:71], v[70:71], v[72:73]
	ds_bpermute_b32 v72, v94, v70
	ds_bpermute_b32 v73, v94, v71
	ds_bpermute_b32 v108, v107, v96
	s_waitcnt lgkmcnt(1)
	v_pk_add_f32 v[94:95], v[70:71], v[72:73]
	global_load_dwordx4 v[70:73], v[88:89], off offset:3072
	s_waitcnt lgkmcnt(0)
	v_add_f32_e32 v108, v96, v108
	v_fmamk_f32 v108, v108, 0x3a800000, v1
	v_mul_f32_e32 v110, 0x4b800000, v108
	v_cmp_gt_f32_e32 vcc, s7, v108
	ds_bpermute_b32 v96, v107, v94
	ds_bpermute_b32 v97, v107, v95
	v_cndmask_b32_e32 v108, v108, v110, vcc
	ds_bpermute_b32 v107, v107, v109
	v_rsq_f32_e32 v108, v108
	s_waitcnt lgkmcnt(1)
	v_pk_add_f32 v[94:95], v[94:95], v[96:97]
	v_mul_f32_e32 v96, 0x45800000, v108
	s_waitcnt lgkmcnt(0)
	v_add_f32_e32 v107, v109, v107
	v_cndmask_b32_e32 v96, v108, v96, vcc
	v_mov_b32_e32 v108, v78
	v_mov_b32_e32 v109, v80
	v_pk_mul_f32 v[108:109], v[108:109], v[96:97] op_sel_hi:[1,0]
	v_mov_b32_e32 v80, v79
	v_pk_mul_f32 v[78:79], v[80:81], v[96:97] op_sel_hi:[1,0]
	s_waitcnt vmcnt(3)
	v_mov_b32_e32 v110, v58
	v_mov_b32_e32 v111, v60
	v_pk_mul_f32 v[108:109], v[110:111], v[108:109]
	v_mov_b32_e32 v80, v59
	v_mov_b32_e32 v81, v61
	v_pk_mul_f32 v[78:79], v[80:81], v[78:79]
	v_and_b32_sdwa v81, v108, v106 dst_sel:DWORD dst_unused:UNUSED_PAD src0_sel:WORD_1 src1_sel:DWORD
	v_add3_u32 v81, v108, v81, s18
	v_and_b32_sdwa v97, v79, v106 dst_sel:DWORD dst_unused:UNUSED_PAD src0_sel:WORD_1 src1_sel:DWORD
	v_and_b32_sdwa v108, v78, v106 dst_sel:DWORD dst_unused:UNUSED_PAD src0_sel:WORD_1 src1_sel:DWORD
	v_and_b32_sdwa v80, v109, v106 dst_sel:DWORD dst_unused:UNUSED_PAD src0_sel:WORD_1 src1_sel:DWORD
	v_add3_u32 v79, v79, v97, s18
	v_add3_u32 v78, v78, v108, s18
	v_add3_u32 v80, v109, v80, s18
	v_and_b32_e32 v79, 0xffff0000, v79
	v_and_b32_e32 v78, 0xffff0000, v78
	v_or_b32_sdwa v79, v79, v80 dst_sel:DWORD dst_unused:UNUSED_PAD src0_sel:DWORD src1_sel:WORD_1
	v_or_b32_sdwa v78, v78, v81 dst_sel:DWORD dst_unused:UNUSED_PAD src0_sel:DWORD src1_sel:WORD_1
	global_store_dwordx2 v[90:91], v[78:79], off sc1
	v_mov_b32_e32 v78, v74
	v_mov_b32_e32 v79, v76
	v_pk_mul_f32 v[78:79], v[78:79], v[96:97] op_sel_hi:[1,0]
	s_waitcnt vmcnt(3)
	v_mov_b32_e32 v80, v62
	v_mov_b32_e32 v81, v64
	v_mov_b32_e32 v76, v75
	v_pk_mul_f32 v[78:79], v[80:81], v[78:79]
	v_pk_mul_f32 v[74:75], v[76:77], v[96:97] op_sel_hi:[1,0]
	v_mov_b32_e32 v76, v63
	v_mov_b32_e32 v77, v65
	v_pk_mul_f32 v[74:75], v[76:77], v[74:75]
	v_and_b32_sdwa v76, v79, v106 dst_sel:DWORD dst_unused:UNUSED_PAD src0_sel:WORD_1 src1_sel:DWORD
	v_and_b32_sdwa v77, v78, v106 dst_sel:DWORD dst_unused:UNUSED_PAD src0_sel:WORD_1 src1_sel:DWORD
	v_add3_u32 v77, v78, v77, s18
	v_add3_u32 v76, v79, v76, s18
	v_and_b32_sdwa v78, v75, v106 dst_sel:DWORD dst_unused:UNUSED_PAD src0_sel:WORD_1 src1_sel:DWORD
	v_and_b32_sdwa v79, v74, v106 dst_sel:DWORD dst_unused:UNUSED_PAD src0_sel:WORD_1 src1_sel:DWORD
	v_add3_u32 v75, v75, v78, s18
	v_add3_u32 v74, v74, v79, s18
	v_and_b32_e32 v75, 0xffff0000, v75
	v_and_b32_e32 v74, 0xffff0000, v74
	v_or_b32_sdwa v75, v75, v76 dst_sel:DWORD dst_unused:UNUSED_PAD src0_sel:DWORD src1_sel:WORD_1
	v_or_b32_sdwa v74, v74, v77 dst_sel:DWORD dst_unused:UNUSED_PAD src0_sel:DWORD src1_sel:WORD_1
	global_store_dwordx2 v[90:91], v[74:75], off offset:512 sc1
	v_mov_b32_e32 v74, v54
	v_mov_b32_e32 v75, v56
	v_pk_mul_f32 v[74:75], v[74:75], v[96:97] op_sel_hi:[1,0]
	s_waitcnt vmcnt(3)
	v_mov_b32_e32 v76, v66
	v_mov_b32_e32 v77, v68
	v_mov_b32_e32 v56, v55
	v_pk_mul_f32 v[74:75], v[76:77], v[74:75]
	v_pk_mul_f32 v[54:55], v[56:57], v[96:97] op_sel_hi:[1,0]
	v_mov_b32_e32 v56, v67
	v_mov_b32_e32 v57, v69
	v_pk_mul_f32 v[54:55], v[56:57], v[54:55]
	v_and_b32_sdwa v56, v75, v106 dst_sel:DWORD dst_unused:UNUSED_PAD src0_sel:WORD_1 src1_sel:DWORD
	v_and_b32_sdwa v57, v74, v106 dst_sel:DWORD dst_unused:UNUSED_PAD src0_sel:WORD_1 src1_sel:DWORD
	v_add3_u32 v57, v74, v57, s18
	v_add3_u32 v56, v75, v56, s18
	v_and_b32_sdwa v74, v55, v106 dst_sel:DWORD dst_unused:UNUSED_PAD src0_sel:WORD_1 src1_sel:DWORD
	v_and_b32_sdwa v75, v54, v106 dst_sel:DWORD dst_unused:UNUSED_PAD src0_sel:WORD_1 src1_sel:DWORD
	v_add3_u32 v55, v55, v74, s18
	v_add3_u32 v54, v54, v75, s18
	v_and_b32_e32 v55, 0xffff0000, v55
	v_and_b32_e32 v54, 0xffff0000, v54
	v_pk_mul_f32 v[50:51], v[50:51], v[96:97] op_sel_hi:[1,0]
	v_or_b32_sdwa v55, v55, v56 dst_sel:DWORD dst_unused:UNUSED_PAD src0_sel:DWORD src1_sel:WORD_1
	v_or_b32_sdwa v54, v54, v57 dst_sel:DWORD dst_unused:UNUSED_PAD src0_sel:DWORD src1_sel:WORD_1
	s_waitcnt vmcnt(2)
	v_pk_mul_f32 v[50:51], v[70:71], v[50:51]
	global_store_dwordx2 v[90:91], v[54:55], off offset:1024 sc1
	v_and_b32_sdwa v55, v50, v106 dst_sel:DWORD dst_unused:UNUSED_PAD src0_sel:WORD_1 src1_sel:DWORD
	v_and_b32_sdwa v54, v51, v106 dst_sel:DWORD dst_unused:UNUSED_PAD src0_sel:WORD_1 src1_sel:DWORD
	v_add3_u32 v50, v50, v55, s18
	v_add3_u32 v51, v51, v54, s18
	v_lshrrev_b32_e32 v50, 16, v50
	v_and_or_b32 v74, v51, s19, v50
	v_mul_f32_e32 v97, v52, v96
	v_pk_mov_b32 v[50:51], v[52:53], v[72:73] op_sel:[1,0]
	v_mov_b32_e32 v56, v59
	v_pk_mul_f32 v[76:77], v[50:51], v[96:97]
	v_mov_b32_e32 v57, v61
	v_mov_b32_e32 v52, v43
	v_mov_b32_e32 v53, v45
	v_mov_b32_e32 v59, v60
	v_mov_b32_e32 v43, v44
	v_mov_b32_e32 v60, v63
	v_mov_b32_e32 v61, v65
	v_mov_b32_e32 v44, v47
	v_mov_b32_e32 v45, v49
	v_mov_b32_e32 v63, v64
	v_mov_b32_e32 v47, v48
	v_mov_b32_e32 v64, v67
	v_mov_b32_e32 v65, v69
	v_mov_b32_e32 v48, v39
	v_mov_b32_e32 v49, v41
	v_mov_b32_e32 v67, v68
	v_mov_b32_e32 v39, v40
	v_mov_b32_e32 v40, v35
	v_mov_b32_e32 v41, v37
	v_mov_b32_e32 v68, v70
	v_mov_b32_e32 v69, v72
	v_mov_b32_e32 v35, v36
	v_mov_b32_e32 v36, v31
	v_mov_b32_e32 v37, v33
	v_mov_b32_e32 v31, v32
	v_mov_b32_e32 v32, v27
	v_mov_b32_e32 v33, v29
	v_mov_b32_e32 v27, v28
	v_mov_b32_e32 v28, v23
	v_mov_b32_e32 v29, v25
	v_mov_b32_e32 v23, v24
	v_mov_b32_e32 v24, v19
	v_mov_b32_e32 v25, v21
	v_mov_b32_e32 v19, v20
	v_mov_b32_e32 v20, v15
	v_mov_b32_e32 v21, v17
	v_mov_b32_e32 v15, v16
	v_mov_b32_e32 v16, v11
	v_mov_b32_e32 v17, v13
	v_mov_b32_e32 v11, v12
	v_mov_b32_e32 v12, v7
	v_mov_b32_e32 v13, v9
	v_mov_b32_e32 v7, v8
	v_mov_b32_e32 v8, v3
	v_mov_b32_e32 v9, v5
	v_mov_b32_e32 v3, v4
	v_mov_b64_e32 v[96:97], v[90:91]
	v_mov_b32_e32 v4, v71
	s_branch .LBB0_17
